# v25 plus redundant early vmcnt drain after the Q loads removed in the MLA block prologue (folded into the pre-barrier wait)
# speedup vs baseline: 1.0043x; 1.0012x over previous
.LBB0_539:
	s_ashr_i32 s4, s2, 4
	s_and_b32 s25, s2, 15
	s_mul_i32 s1, s4, 0x1818000
	s_mul_hi_i32 s0, s4, 0x1818000
	s_add_u32 s1, s17, s1
	s_addc_u32 s0, s18, s0
	s_mul_i32 s2, s25, 0x180
	s_add_u32 s8, s1, s2
	s_addc_u32 s9, s0, 0
	s_mul_i32 s0, s4, 0x1010000
	s_mul_hi_i32 s1, s4, 0x1010000
	s_add_u32 s2, s19, s0
	s_addc_u32 s5, s44, s1
	s_lshl_b32 s30, s25, 8
	s_add_u32 s10, s2, s30
	s_addc_u32 s11, s5, 0
	s_mul_hi_i32 s5, s4, 0x80800
	s_mul_i32 s4, s4, 0x80800
	s_add_u32 s12, s45, s4
	s_addc_u32 s13, s46, s5
	s_add_u32 s2, s47, s0
	s_addc_u32 s6, s48, s1
	v_mov_b32_e32 v213, v0
	s_add_u32 s14, s2, s30
	s_addc_u32 s15, s6, 0
	v_readfirstlane_b32 s21, v213
	v_and_b32_e32 v217, 63, v213
	v_lshlrev_b32_e32 v2, 1, v213
	s_ashr_i32 s2, s21, 6
	v_lshlrev_b32_e32 v220, 3, v217
	s_waitcnt vmcnt(0)
	v_lshlrev_b32_e32 v69, 4, v217
	v_and_b32_e32 v2, 32, v2
	v_and_b32_e32 v68, 24, v220
	v_and_or_b32 v2, v69, s56, v2
	s_waitcnt lgkmcnt(0)
	v_and_b32_e32 v4, 0x100, v220
	s_lshl_b32 s31, s2, 11
	s_and_b32 s21, s21, 0x3fffffc0
	v_or3_b32 v14, v2, v4, v68
	v_or_b32_e32 v2, s31, v69
	s_lshl_b32 s21, s21, 2
	v_or_b32_e32 v5, 0x400, v2
	v_ashrrev_i32_e32 v2, 8, v2
	s_add_i32 s23, s21, 0
	v_and_b32_e32 v4, 0xf0, v69
	v_lshlrev_b32_e32 v6, 4, v2
	s_movk_i32 s21, 0xb0
	v_lshlrev_b32_e32 v70, 11, v2
	v_ashrrev_i32_e32 v2, 8, v5
	v_bitop3_b32 v4, v6, v4, s21 bitop3:0x6c
	v_xor_b32_e32 v6, v2, v213
	v_lshlrev_b32_e32 v71, 11, v2
	v_lshlrev_b32_e32 v2, 3, v6
	v_and_b32_e32 v73, 0x78, v2
	s_lshl_b32 s21, s2, 3
	v_lshrrev_b32_e32 v2, 1, v213
	v_bfe_u32 v75, v213, 2, 2
	s_and_b32 s40, s21, -16
	v_and_b32_e32 v76, 8, v2
	s_lshl_b32 s21, s2, 2
	s_and_b32 s41, s21, 4
	v_or3_b32 v2, v76, v75, s40
	v_or_b32_e32 v2, s41, v2
	v_and_b32_e32 v74, 32, v213
	v_lshlrev_b32_e32 v2, 11, v2
	v_lshrrev_b32_e32 v5, 4, v5
	v_or3_b32 v8, v68, v74, v2
	v_and_b32_e32 v5, 0x60, v5
	v_or3_b32 v10, v68, v5, v2
	s_lshl_b32 s36, s2, 10
	v_ashrrev_i32_e32 v9, 31, v8
	s_add_i32 s21, s31, 0
	v_lshrrev_b32_e32 v72, 1, v4
	v_or_b32_e32 v2, s36, v69
	v_lshl_add_u64 v[8:9], v[8:9], 1, s[14:15]
	s_mov_b32 m0, s21
	v_ashrrev_i32_e32 v11, 31, v10
	v_or_b32_e32 v4, v72, v70
	v_ashrrev_i32_e32 v5, 1, v2
	v_lshrrev_b32_e32 v2, 5, v2
	global_load_lds_dwordx4 v[8:9], off
	v_lshl_add_u64 v[8:9], v[10:11], 1, s[14:15]
	s_add_i32 s15, s21, 0x400
	s_lshl_b32 s7, s3, 8
	s_lshl_b32 s6, s2, 5
	v_or_b32_e32 v6, v73, v71
	v_and_b32_e32 v77, 0xffffffc0, v5
	v_bitop3_b32 v78, v2, 56, v220 bitop3:0x48
	s_mov_b32 m0, s15
	v_ashrrev_i32_e32 v5, 31, v4
	s_add_i32 s33, s21, 0x8000
	s_add_i32 s24, s7, s6
	v_or_b32_e32 v12, v78, v77
	global_load_lds_dwordx4 v[8:9], off
	v_lshl_add_u64 v[4:5], v[4:5], 1, s[10:11]
	s_mov_b32 m0, s33
	v_ashrrev_i32_e32 v7, 31, v6
	s_add_i32 s50, s21, 0x8400
	s_sub_i32 s52, s21, s36
	v_and_b32_e32 v215, 31, v213
	s_add_i32 s6, s24, 0xffffff10
	global_load_lds_dwordx4 v[4:5], off
	v_lshl_add_u64 v[4:5], v[6:7], 1, s[10:11]
	s_mov_b32 m0, s50
	v_ashrrev_i32_e32 v13, 31, v12
	s_add_i32 s51, s52, 0x10000
	v_add_u32_e32 v223, s6, v215
	global_load_lds_dwordx4 v[4:5], off
	v_lshl_add_u64 v[4:5], v[12:13], 1, s[12:13]
	s_mov_b32 m0, s51
	v_bfe_u32 v214, v213, 5, 1
	global_load_lds_dwordx4 v[4:5], off
	v_max_i32_e32 v2, 0, v223
	v_mov_b64_e32 v[4:5], s[8:9]
	v_mad_u64_u32 v[4:5], s[8:9], v2, s91, v[4:5]
	v_lshlrev_b32_e32 v2, 4, v214
	v_lshl_add_u64 v[4:5], v[4:5], 0, v[2:3]
	global_load_dwordx4 v[176:179], v[4:5], off
	global_load_dwordx4 v[172:175], v[4:5], off offset:32
	global_load_dwordx4 v[168:171], v[4:5], off offset:64
	global_load_dwordx4 v[164:167], v[4:5], off offset:96
	global_load_dwordx4 v[160:163], v[4:5], off offset:128
	global_load_dwordx4 v[156:159], v[4:5], off offset:160
	global_load_dwordx4 v[152:155], v[4:5], off offset:192
	global_load_dwordx4 v[148:151], v[4:5], off offset:224
	global_load_dwordx4 v[144:147], v[4:5], off offset:256
	global_load_dwordx4 v[140:143], v[4:5], off offset:288
	global_load_dwordx4 v[136:139], v[4:5], off offset:320
	global_load_dwordx4 v[132:135], v[4:5], off offset:352
	s_add_i32 s23, s23, 0x14000
	s_cmp_lg_u32 0, -1
	s_cselect_b32 s8, 0, 0
	s_cmp_eq_u32 s3, 0
	s_cselect_b64 s[36:37], -1, 0
	s_cmp_lg_u32 s3, 0
	v_lshlrev_b32_e32 v216, 2, v214
	v_add_u32_e32 v221, s8, v14
	s_cselect_b64 s[8:9], -1, 0
	v_bitop3_b32 v4, v214, v213, 15 bitop3:0x78
	v_lshlrev_b32_e32 v79, 3, v215
	s_mov_b64 s[10:11], -1
	s_and_b64 vcc, exec, s[8:9]
	v_cmp_gt_u32_e64 s[38:39], 32, v217
	v_lshlrev_b32_e32 v225, 4, v4
	v_lshl_add_u32 v226, v215, 8, 0
	v_and_b32_e32 v224, 0x70, v79
	v_lshl_add_u32 v219, v215, 2, s23
	v_lshl_add_u32 v218, v216, 2, s23
	s_waitcnt vmcnt(0) lgkmcnt(0)
	s_barrier
	s_cbranch_vccz .LBB0_569
	s_lshl_b32 s23, s3, 2
	v_lshlrev_b32_e32 v4, 7, v215
	s_add_i32 s3, 0, 0x10000
	v_add_u32_e32 v227, s3, v4
	s_movk_i32 s3, 0x70
	s_add_i32 s52, s52, 0x12000
	s_add_i32 s14, s6, 31
	v_bitop3_b32 v228, v2, v79, s3 bitop3:0x78
	s_add_i32 s3, 0, 0x12000
	v_add_u32_e32 v232, s3, v4
	v_add_u32_e32 v4, v77, v78
	s_add_u32 s10, s0, s30
	v_ashrrev_i32_e32 v5, 31, v4
	s_addc_u32 s11, s1, 0
	s_add_i32 s41, s41, s40
	v_lshl_add_u64 v[188:189], v[4:5], 1, s[4:5]
	v_add_u32_e32 v4, s41, v76
	v_add_lshl_u32 v6, v4, v75, 11
	v_or_b32_e32 v4, v6, v74
	v_add_u32_e32 v4, v4, v68
	v_ashrrev_i32_e32 v5, 31, v4
	s_addk_i32 s31, 0x400
	v_lshl_add_u64 v[190:191], v[4:5], 1, s[10:11]
	v_add_u32_e32 v4, s31, v69
	v_lshrrev_b32_e32 v4, 4, v4
	v_and_b32_e32 v4, 0x60, v4
	v_or3_b32 v4, v6, v4, v68
	v_ashrrev_i32_e32 v5, 31, v4
	v_lshl_add_u64 v[192:193], v[4:5], 1, s[10:11]
	v_add_u32_e32 v4, v72, v70
	v_ashrrev_i32_e32 v5, 31, v4
	v_lshl_add_u64 v[194:195], v[4:5], 1, s[10:11]
	v_add_u32_e32 v4, v71, v73
	v_ashrrev_i32_e32 v5, 31, v4
	v_lshl_add_u64 v[196:197], v[4:5], 1, s[10:11]
	v_add_u32_e32 v4, s24, v215
	v_mov_b32_e32 v18, v3
	v_mov_b32_e32 v19, v3
	v_sub_u32_e32 v233, v4, v216
	v_mov_b32_e32 v4, v3
	v_mov_b32_e32 v5, v3
	v_mov_b32_e32 v6, v3
	v_mov_b32_e32 v7, v3
	v_mov_b32_e32 v8, v3
	v_mov_b32_e32 v9, v3
	v_mov_b32_e32 v10, v3
	v_mov_b32_e32 v11, v3
	v_mov_b32_e32 v12, v3
	v_mov_b32_e32 v13, v3
	v_mov_b32_e32 v14, v3
	v_mov_b32_e32 v15, v3
	v_mov_b32_e32 v16, v3
	v_mov_b32_e32 v17, v3
	v_mov_b32_e32 v234, 0
	v_mov_b64_e32 v[66:67], v[18:19]
	v_mov_b64_e32 v[34:35], v[18:19]
	v_mov_b64_e32 v[50:51], v[18:19]
	v_bitop3_b32 v229, v2, v224, 32 bitop3:0x36
	v_bitop3_b32 v230, v2, v224, 64 bitop3:0x36
	v_bitop3_b32 v231, v2, v224, s26 bitop3:0x36
	s_mov_b32 s53, 0
	s_mov_b32 s24, 63
	s_add_i32 s54, s21, 0x4400
	s_add_i32 s55, s21, 0xc400
	v_mov_b64_e32 v[64:65], v[16:17]
	v_mov_b64_e32 v[62:63], v[14:15]
	v_mov_b64_e32 v[60:61], v[12:13]
	v_mov_b64_e32 v[58:59], v[10:11]
	v_mov_b64_e32 v[56:57], v[8:9]
	v_mov_b64_e32 v[54:55], v[6:7]
	v_mov_b64_e32 v[52:53], v[4:5]
	v_mov_b64_e32 v[32:33], v[16:17]
	v_mov_b64_e32 v[30:31], v[14:15]
	v_mov_b64_e32 v[28:29], v[12:13]
	v_mov_b64_e32 v[26:27], v[10:11]
	v_mov_b64_e32 v[24:25], v[8:9]
	v_mov_b64_e32 v[22:23], v[6:7]
	v_mov_b64_e32 v[20:21], v[4:5]
	v_mov_b64_e32 v[48:49], v[16:17]
	v_mov_b64_e32 v[46:47], v[14:15]
	v_mov_b64_e32 v[44:45], v[12:13]
	v_mov_b64_e32 v[42:43], v[10:11]
	v_mov_b64_e32 v[40:41], v[8:9]
	v_mov_b64_e32 v[38:39], v[6:7]
	v_mov_b64_e32 v[36:37], v[4:5]
	s_mov_b32 s30, 0
	v_mov_b32_e32 v222, 0
	v_mov_b32_e32 v68, 0
	v_mov_b32_e32 v69, v234
	v_mov_b32_e32 v70, v234
	v_mov_b32_e32 v71, v234
	v_mov_b32_e32 v72, v234
	v_mov_b32_e32 v73, v234
	v_mov_b32_e32 v74, v234
	v_mov_b32_e32 v75, v234
	v_mov_b32_e32 v76, v234
	v_mov_b32_e32 v77, v234
	v_mov_b32_e32 v78, v234
	v_mov_b32_e32 v79, v234
	v_mov_b32_e32 v80, v234
	v_mov_b32_e32 v81, v234
	v_mov_b32_e32 v82, v234
	v_mov_b32_e32 v83, v234
	s_branch .LBB0_544
